# EF1: at every grid seam the workgroup that finds 8 others of its XCD still missing issues an early L2 write-back (buffer_wbl2 sc1) while it waits
# baseline (speedup 1.0000x reference)
; __device__ __forceinline__ unsigned xb_ld(unsigned* p)              { return __hip_atomic_load(p, __ATOMIC_RELAXED, __HIP_MEMORY_SCOPE_AGENT); }
; __device__ __forceinline__ unsigned xb_add(unsigned* p, unsigned v) { return __hip_atomic_fetch_add(p, v, __ATOMIC_RELAXED, __HIP_MEMORY_SCOPE_AGENT); }
; #define XB_SPIN(cond, bar) do { unsigned _sp = 0; while (cond) { __builtin_amdgcn_s_sleep(1); \
;     if ((++_sp & 255u) == 0u) { if (xb_ld(&(bar)[XB_TMO])) break; if (_sp > XB_SPIN_CAP) { atomicAdd(&(bar)[XB_TMO], 1u); break; } } } } while (0)
; __device__ __forceinline__ void xcd_barrier(const XcdBarrier& b) {
;     ...
;         unsigned nloc = b.st[0], nx = b.st[1];
;         if (nloc == 0u) { xcd_barrier_complete(bar, b.x, nloc, nx); b.st[0] = nloc; b.st[1] = nx; }
;         const unsigned old = xb_add(&bar[XB_XSUB(b.x)], 1u);
;         const unsigned gen = old / nloc;
;         if (old + 1u == (gen + 1u) * nloc) {
;             __builtin_amdgcn_fence(__ATOMIC_RELEASE, "agent");
;             asm volatile("s_waitcnt vmcnt(0)" ::: "memory");
;             const unsigned og = xb_add(&bar[XB_TOP], 1u);
;             const unsigned tg = og / nx;
;             if (og + 1u == (tg + 1u) * nx) xb_add(&bar[XB_TOPGEN], 1u);
;             else XB_SPIN(xb_ld(&bar[XB_TOPGEN]) == tg, bar);
;             __builtin_amdgcn_fence(__ATOMIC_ACQUIRE, "agent");
;             xb_add(&bar[XB_XGEN(b.x)], 1u);
;             asm volatile("s_waitcnt vmcnt(0)" ::: "memory");
;         } else {
;             XB_SPIN(xb_ld(&bar[XB_XGEN(b.x)]) == gen, bar);
.LBB0_53:
	s_lshl_b32 s3, s8, 8
	s_add_u32 s9, s12, s3
	s_addc_u32 s3, s13, 0
	v_mov_b32_e32 v1, s9
	v_add_co_u32_e32 v6, vcc, 0x1000, v1
	v_mov_b32_e32 v1, s3
	s_nop 0
	v_addc_co_u32_e32 v7, vcc, 0, v1, vcc
	v_mov_b32_e32 v1, 1
	flat_atomic_add v1, v[6:7], v1 offset:1024 sc0
	v_cvt_f32_u32_e32 v3, v4
	v_sub_u32_e32 v5, 0, v4
	v_rcp_iflag_f32_e32 v3, v3
	s_nop 0
	v_mul_f32_e32 v3, 0x4f7ffffe, v3
	v_cvt_u32_f32_e32 v3, v3
	v_mul_lo_u32 v5, v5, v3
	v_mul_hi_u32 v5, v3, v5
	v_add_u32_e32 v3, v3, v5
	s_waitcnt vmcnt(0) lgkmcnt(0)
	v_mul_hi_u32 v3, v1, v3
	v_mul_lo_u32 v5, v3, v4
	v_add_u32_e32 v6, 1, v1
	v_sub_u32_e32 v1, v1, v5
	v_add_u32_e32 v7, 1, v3
	v_cmp_ge_u32_e32 vcc, v1, v4
	v_sub_u32_e32 v5, v1, v4
	s_nop 0
	v_cndmask_b32_e32 v3, v3, v7, vcc
	v_cndmask_b32_e32 v1, v1, v5, vcc
	v_add_u32_e32 v5, 1, v3
	v_cmp_ge_u32_e32 vcc, v1, v4
	s_nop 1
	v_cndmask_b32_e32 v1, v3, v5, vcc
	v_mad_u64_u32 v[4:5], s[4:5], v4, v1, v[4:5]
	v_cmp_ne_u32_e32 vcc, v6, v4
	s_and_saveexec_b64 s[4:5], vcc
	s_xor_b64 s[4:5], exec, s[4:5]
	s_cbranch_execz .LBB0_66
	v_sub_u32_e32 v2, v4, v6
	v_cmp_eq_u32_e32 vcc, 8, v2
	s_cbranch_vccz .Lef1_0_0
	buffer_wbl2 sc1
.Lef1_0_0:
	v_mov_b32_e32 v2, s9
	v_add_co_u32_e32 v2, vcc, 0x2000, v2
	v_mov_b32_e32 v3, s3
	s_nop 0
	v_addc_co_u32_e32 v3, vcc, 0, v3, vcc
	flat_load_dword v2, v[2:3] offset:1024 sc1
	s_add_u32 s30, s9, 0x2400
	s_addc_u32 s31, s3, 0
	s_waitcnt vmcnt(0) lgkmcnt(0)
	v_cmp_eq_u32_e32 vcc, v2, v1
	s_and_saveexec_b64 s[14:15], vcc
	s_cbranch_execz .LBB0_65
	s_mov_b32 s33, 1
	s_mov_b64 s[34:35], 0
	s_branch .LBB0_57

; __device__ __forceinline__ unsigned xb_ld(unsigned* p)              { return __hip_atomic_load(p, __ATOMIC_RELAXED, __HIP_MEMORY_SCOPE_AGENT); }
; __device__ __forceinline__ unsigned xb_add(unsigned* p, unsigned v) { return __hip_atomic_fetch_add(p, v, __ATOMIC_RELAXED, __HIP_MEMORY_SCOPE_AGENT); }
; #define XB_SPIN(cond, bar) do { unsigned _sp = 0; while (cond) { __builtin_amdgcn_s_sleep(1); \
;     if ((++_sp & 255u) == 0u) { if (xb_ld(&(bar)[XB_TMO])) break; if (_sp > XB_SPIN_CAP) { atomicAdd(&(bar)[XB_TMO], 1u); break; } } } } while (0)
; __device__ __forceinline__ void xcd_barrier(const XcdBarrier& b) {
;     ...
;         unsigned nloc = b.st[0], nx = b.st[1];
;         if (nloc == 0u) { xcd_barrier_complete(bar, b.x, nloc, nx); b.st[0] = nloc; b.st[1] = nx; }
;         const unsigned old = xb_add(&bar[XB_XSUB(b.x)], 1u);
;         const unsigned gen = old / nloc;
;         if (old + 1u == (gen + 1u) * nloc) {
;             __builtin_amdgcn_fence(__ATOMIC_RELEASE, "agent");
;             asm volatile("s_waitcnt vmcnt(0)" ::: "memory");
;             const unsigned og = xb_add(&bar[XB_TOP], 1u);
;             const unsigned tg = og / nx;
;             if (og + 1u == (tg + 1u) * nx) xb_add(&bar[XB_TOPGEN], 1u);
;             else XB_SPIN(xb_ld(&bar[XB_TOPGEN]) == tg, bar);
;             __builtin_amdgcn_fence(__ATOMIC_ACQUIRE, "agent");
;             xb_add(&bar[XB_XGEN(b.x)], 1u);
;             asm volatile("s_waitcnt vmcnt(0)" ::: "memory");
;         } else {
;             XB_SPIN(xb_ld(&bar[XB_XGEN(b.x)]) == gen, bar);
.LBB0_130:
	s_lshl_b32 s3, s8, 8
	s_add_u32 s9, s10, s3
	s_addc_u32 s3, s11, 0
	v_mov_b32_e32 v1, s9
	v_add_co_u32_e32 v6, vcc, 0x1000, v1
	v_mov_b32_e32 v1, s3
	s_nop 0
	v_addc_co_u32_e32 v7, vcc, 0, v1, vcc
	v_mov_b32_e32 v1, 1
	flat_atomic_add v1, v[6:7], v1 offset:1024 sc0
	v_cvt_f32_u32_e32 v3, v4
	v_sub_u32_e32 v5, 0, v4
	v_rcp_iflag_f32_e32 v3, v3
	s_nop 0
	v_mul_f32_e32 v3, 0x4f7ffffe, v3
	v_cvt_u32_f32_e32 v3, v3
	v_mul_lo_u32 v5, v5, v3
	v_mul_hi_u32 v5, v3, v5
	v_add_u32_e32 v3, v3, v5
	s_waitcnt vmcnt(0) lgkmcnt(0)
	v_mul_hi_u32 v3, v1, v3
	v_mul_lo_u32 v5, v3, v4
	v_add_u32_e32 v6, 1, v1
	v_sub_u32_e32 v1, v1, v5
	v_add_u32_e32 v7, 1, v3
	v_cmp_ge_u32_e32 vcc, v1, v4
	v_sub_u32_e32 v5, v1, v4
	s_nop 0
	v_cndmask_b32_e32 v3, v3, v7, vcc
	v_cndmask_b32_e32 v1, v1, v5, vcc
	v_add_u32_e32 v5, 1, v3
	v_cmp_ge_u32_e32 vcc, v1, v4
	s_nop 1
	v_cndmask_b32_e32 v1, v3, v5, vcc
	v_mad_u64_u32 v[4:5], s[4:5], v4, v1, v[4:5]
	v_cmp_ne_u32_e32 vcc, v6, v4
	s_and_saveexec_b64 s[4:5], vcc
	s_xor_b64 s[4:5], exec, s[4:5]
	s_cbranch_execz .LBB0_143
	v_sub_u32_e32 v2, v4, v6
	v_cmp_eq_u32_e32 vcc, 8, v2
	s_cbranch_vccz .Lef1_1_0
	buffer_wbl2 sc1
.Lef1_1_0:
	v_mov_b32_e32 v2, s9
	v_add_co_u32_e32 v2, vcc, 0x2000, v2
	v_mov_b32_e32 v3, s3
	s_nop 0
	v_addc_co_u32_e32 v3, vcc, 0, v3, vcc
	flat_load_dword v2, v[2:3] offset:1024 sc1
	s_add_u32 s14, s9, 0x2400
	s_addc_u32 s15, s3, 0
	s_waitcnt vmcnt(0) lgkmcnt(0)
	v_cmp_eq_u32_e32 vcc, v2, v1
	s_and_saveexec_b64 s[12:13], vcc
	s_cbranch_execz .LBB0_142
	s_mov_b32 s33, 1
	s_mov_b64 s[16:17], 0
	s_branch .LBB0_134

; __device__ __forceinline__ unsigned xb_ld(unsigned* p)              { return __hip_atomic_load(p, __ATOMIC_RELAXED, __HIP_MEMORY_SCOPE_AGENT); }
; __device__ __forceinline__ unsigned xb_add(unsigned* p, unsigned v) { return __hip_atomic_fetch_add(p, v, __ATOMIC_RELAXED, __HIP_MEMORY_SCOPE_AGENT); }
; #define XB_SPIN(cond, bar) do { unsigned _sp = 0; while (cond) { __builtin_amdgcn_s_sleep(1); \
;     if ((++_sp & 255u) == 0u) { if (xb_ld(&(bar)[XB_TMO])) break; if (_sp > XB_SPIN_CAP) { atomicAdd(&(bar)[XB_TMO], 1u); break; } } } } while (0)
; __device__ __forceinline__ void xcd_barrier(const XcdBarrier& b) {
;     ...
;         unsigned nloc = b.st[0], nx = b.st[1];
;         if (nloc == 0u) { xcd_barrier_complete(bar, b.x, nloc, nx); b.st[0] = nloc; b.st[1] = nx; }
;         const unsigned old = xb_add(&bar[XB_XSUB(b.x)], 1u);
;         const unsigned gen = old / nloc;
;         if (old + 1u == (gen + 1u) * nloc) {
;             __builtin_amdgcn_fence(__ATOMIC_RELEASE, "agent");
;             asm volatile("s_waitcnt vmcnt(0)" ::: "memory");
;             const unsigned og = xb_add(&bar[XB_TOP], 1u);
;             const unsigned tg = og / nx;
;             if (og + 1u == (tg + 1u) * nx) xb_add(&bar[XB_TOPGEN], 1u);
;             else XB_SPIN(xb_ld(&bar[XB_TOPGEN]) == tg, bar);
;             __builtin_amdgcn_fence(__ATOMIC_ACQUIRE, "agent");
;             xb_add(&bar[XB_XGEN(b.x)], 1u);
;             asm volatile("s_waitcnt vmcnt(0)" ::: "memory");
;         } else {
;             XB_SPIN(xb_ld(&bar[XB_XGEN(b.x)]) == gen, bar);
.LBB0_354:
	v_readlane_b32 s6, v254, 18
	s_lshl_b32 s6, s6, 2
	s_add_u32 s12, s4, s6
	s_addc_u32 s9, s5, 0
	v_mov_b32_e32 v3, s12
	v_add_co_u32_e32 v6, vcc, 0x1000, v3
	v_mov_b32_e32 v3, s9
	s_nop 0
	v_addc_co_u32_e32 v7, vcc, 0, v3, vcc
	flat_atomic_add v5, v[6:7], v224 offset:1024 sc0
	v_cvt_f32_u32_e32 v3, v4
	v_sub_u32_e32 v6, 0, v4
	v_rcp_iflag_f32_e32 v3, v3
	s_nop 0
	v_mul_f32_e32 v3, 0x4f7ffffe, v3
	v_cvt_u32_f32_e32 v3, v3
	v_mul_lo_u32 v6, v6, v3
	v_mul_hi_u32 v6, v3, v6
	v_add_u32_e32 v3, v3, v6
	s_waitcnt vmcnt(0) lgkmcnt(0)
	v_mul_hi_u32 v3, v5, v3
	v_mul_lo_u32 v6, v3, v4
	v_sub_u32_e32 v6, v5, v6
	v_cmp_ge_u32_e32 vcc, v6, v4
	v_add_u32_e32 v7, 1, v3
	s_nop 0
	v_cndmask_b32_e32 v3, v3, v7, vcc
	v_sub_u32_e32 v7, v6, v4
	v_cndmask_b32_e32 v6, v6, v7, vcc
	v_cmp_ge_u32_e32 vcc, v6, v4
	v_add_u32_e32 v6, 1, v3
	s_nop 0
	v_cndmask_b32_e32 v3, v3, v6, vcc
	v_add_u32_e32 v6, 1, v5
	v_mad_u64_u32 v[4:5], s[6:7], v4, v3, v[4:5]
	v_cmp_ne_u32_e32 vcc, v6, v4
	s_and_saveexec_b64 s[6:7], vcc
	s_xor_b64 s[6:7], exec, s[6:7]
	s_cbranch_execz .LBB0_367
	v_sub_u32_e32 v2, v4, v6
	v_cmp_eq_u32_e32 vcc, 8, v2
	s_cbranch_vccz .Lef1_2_0
	buffer_wbl2 sc1
.Lef1_2_0:
	v_mov_b32_e32 v2, s12
	v_add_co_u32_e32 v4, vcc, 0x2000, v2
	v_mov_b32_e32 v2, s9
	s_nop 0
	v_addc_co_u32_e32 v5, vcc, 0, v2, vcc
	flat_load_dword v2, v[4:5] offset:1024 sc1
	s_add_u32 s34, s12, 0x2400
	s_addc_u32 s35, s9, 0
	s_waitcnt vmcnt(0) lgkmcnt(0)
	v_cmp_eq_u32_e32 vcc, v2, v3
	s_and_saveexec_b64 s[10:11], vcc
	s_cbranch_execz .LBB0_366
	s_mov_b32 s13, 1
	s_mov_b64 s[66:67], 0
	s_branch .LBB0_358

; __device__ __forceinline__ unsigned xb_ld(unsigned* p)              { return __hip_atomic_load(p, __ATOMIC_RELAXED, __HIP_MEMORY_SCOPE_AGENT); }
; __device__ __forceinline__ unsigned xb_add(unsigned* p, unsigned v) { return __hip_atomic_fetch_add(p, v, __ATOMIC_RELAXED, __HIP_MEMORY_SCOPE_AGENT); }
; #define XB_SPIN(cond, bar) do { unsigned _sp = 0; while (cond) { __builtin_amdgcn_s_sleep(1); \
;     if ((++_sp & 255u) == 0u) { if (xb_ld(&(bar)[XB_TMO])) break; if (_sp > XB_SPIN_CAP) { atomicAdd(&(bar)[XB_TMO], 1u); break; } } } } while (0)
; __device__ __forceinline__ void xcd_barrier(const XcdBarrier& b) {
;     ...
;         unsigned nloc = b.st[0], nx = b.st[1];
;         if (nloc == 0u) { xcd_barrier_complete(bar, b.x, nloc, nx); b.st[0] = nloc; b.st[1] = nx; }
;         const unsigned old = xb_add(&bar[XB_XSUB(b.x)], 1u);
;         const unsigned gen = old / nloc;
;         if (old + 1u == (gen + 1u) * nloc) {
;             __builtin_amdgcn_fence(__ATOMIC_RELEASE, "agent");
;             asm volatile("s_waitcnt vmcnt(0)" ::: "memory");
;             const unsigned og = xb_add(&bar[XB_TOP], 1u);
;             const unsigned tg = og / nx;
;             if (og + 1u == (tg + 1u) * nx) xb_add(&bar[XB_TOPGEN], 1u);
;             else XB_SPIN(xb_ld(&bar[XB_TOPGEN]) == tg, bar);
;             __builtin_amdgcn_fence(__ATOMIC_ACQUIRE, "agent");
;             xb_add(&bar[XB_XGEN(b.x)], 1u);
;             asm volatile("s_waitcnt vmcnt(0)" ::: "memory");
;         } else {
;             XB_SPIN(xb_ld(&bar[XB_XGEN(b.x)]) == gen, bar);
.LBB0_443:
	v_readlane_b32 s7, v254, 18
	s_lshl_b32 s7, s7, 2
	s_add_u32 s8, s4, s7
	s_addc_u32 s7, s5, 0
	v_mov_b32_e32 v3, s8
	v_add_co_u32_e32 v6, vcc, 0x1000, v3
	v_mov_b32_e32 v3, s7
	s_nop 0
	v_addc_co_u32_e32 v7, vcc, 0, v3, vcc
	flat_atomic_add v5, v[6:7], v224 offset:1024 sc0
	v_cvt_f32_u32_e32 v3, v4
	v_sub_u32_e32 v6, 0, v4
	v_rcp_iflag_f32_e32 v3, v3
	s_nop 0
	v_mul_f32_e32 v3, 0x4f7ffffe, v3
	v_cvt_u32_f32_e32 v3, v3
	v_mul_lo_u32 v6, v6, v3
	v_mul_hi_u32 v6, v3, v6
	v_add_u32_e32 v3, v3, v6
	s_waitcnt vmcnt(0) lgkmcnt(0)
	v_mul_hi_u32 v3, v5, v3
	v_mul_lo_u32 v6, v3, v4
	v_sub_u32_e32 v6, v5, v6
	v_cmp_ge_u32_e32 vcc, v6, v4
	v_add_u32_e32 v7, 1, v3
	s_nop 0
	v_cndmask_b32_e32 v3, v3, v7, vcc
	v_sub_u32_e32 v7, v6, v4
	v_cndmask_b32_e32 v6, v6, v7, vcc
	v_cmp_ge_u32_e32 vcc, v6, v4
	v_add_u32_e32 v6, 1, v3
	s_nop 0
	v_cndmask_b32_e32 v3, v3, v6, vcc
	v_add_u32_e32 v6, 1, v5
	v_mad_u64_u32 v[4:5], s[10:11], v4, v3, v[4:5]
	v_cmp_ne_u32_e32 vcc, v6, v4
	s_and_saveexec_b64 s[10:11], vcc
	s_xor_b64 s[10:11], exec, s[10:11]
	s_cbranch_execz .LBB0_456
	v_sub_u32_e32 v2, v4, v6
	v_cmp_eq_u32_e32 vcc, 8, v2
	s_cbranch_vccz .Lef1_3_0
	buffer_wbl2 sc1
.Lef1_3_0:
	v_mov_b32_e32 v2, s8
	v_add_co_u32_e32 v4, vcc, 0x2000, v2
	v_mov_b32_e32 v2, s7
	s_nop 0
	v_addc_co_u32_e32 v5, vcc, 0, v2, vcc
	flat_load_dword v2, v[4:5] offset:1024 sc1
	s_add_u32 s66, s8, 0x2400
	s_addc_u32 s67, s7, 0
	s_waitcnt vmcnt(0) lgkmcnt(0)
	v_cmp_eq_u32_e32 vcc, v2, v3
	s_and_saveexec_b64 s[34:35], vcc
	s_cbranch_execz .LBB0_455
	s_mov_b32 s9, 1
	s_mov_b64 s[68:69], 0
	s_branch .LBB0_447

; __device__ __forceinline__ unsigned xb_ld(unsigned* p)              { return __hip_atomic_load(p, __ATOMIC_RELAXED, __HIP_MEMORY_SCOPE_AGENT); }
; __device__ __forceinline__ unsigned xb_add(unsigned* p, unsigned v) { return __hip_atomic_fetch_add(p, v, __ATOMIC_RELAXED, __HIP_MEMORY_SCOPE_AGENT); }
; #define XB_SPIN(cond, bar) do { unsigned _sp = 0; while (cond) { __builtin_amdgcn_s_sleep(1); \
;     if ((++_sp & 255u) == 0u) { if (xb_ld(&(bar)[XB_TMO])) break; if (_sp > XB_SPIN_CAP) { atomicAdd(&(bar)[XB_TMO], 1u); break; } } } } while (0)
; __device__ __forceinline__ void xcd_barrier(const XcdBarrier& b) {
;     ...
;         unsigned nloc = b.st[0], nx = b.st[1];
;         if (nloc == 0u) { xcd_barrier_complete(bar, b.x, nloc, nx); b.st[0] = nloc; b.st[1] = nx; }
;         const unsigned old = xb_add(&bar[XB_XSUB(b.x)], 1u);
;         const unsigned gen = old / nloc;
;         if (old + 1u == (gen + 1u) * nloc) {
;             __builtin_amdgcn_fence(__ATOMIC_RELEASE, "agent");
;             asm volatile("s_waitcnt vmcnt(0)" ::: "memory");
;             const unsigned og = xb_add(&bar[XB_TOP], 1u);
;             const unsigned tg = og / nx;
;             if (og + 1u == (tg + 1u) * nx) xb_add(&bar[XB_TOPGEN], 1u);
;             else XB_SPIN(xb_ld(&bar[XB_TOPGEN]) == tg, bar);
;             __builtin_amdgcn_fence(__ATOMIC_ACQUIRE, "agent");
;             xb_add(&bar[XB_XGEN(b.x)], 1u);
;             asm volatile("s_waitcnt vmcnt(0)" ::: "memory");
;         } else {
;             XB_SPIN(xb_ld(&bar[XB_XGEN(b.x)]) == gen, bar);
.LBB0_524:
	v_readlane_b32 s6, v254, 18
	s_lshl_b32 s6, s6, 2
	s_add_u32 s7, s4, s6
	s_addc_u32 s6, s5, 0
	v_mov_b32_e32 v3, s7
	v_add_co_u32_e32 v6, vcc, 0x1000, v3
	v_mov_b32_e32 v3, s6
	s_nop 0
	v_addc_co_u32_e32 v7, vcc, 0, v3, vcc
	flat_atomic_add v5, v[6:7], v224 offset:1024 sc0
	v_cvt_f32_u32_e32 v3, v4
	v_sub_u32_e32 v6, 0, v4
	v_rcp_iflag_f32_e32 v3, v3
	s_nop 0
	v_mul_f32_e32 v3, 0x4f7ffffe, v3
	v_cvt_u32_f32_e32 v3, v3
	v_mul_lo_u32 v6, v6, v3
	v_mul_hi_u32 v6, v3, v6
	v_add_u32_e32 v3, v3, v6
	s_waitcnt vmcnt(0) lgkmcnt(0)
	v_mul_hi_u32 v3, v5, v3
	v_mul_lo_u32 v6, v3, v4
	v_sub_u32_e32 v6, v5, v6
	v_cmp_ge_u32_e32 vcc, v6, v4
	v_add_u32_e32 v7, 1, v3
	s_nop 0
	v_cndmask_b32_e32 v3, v3, v7, vcc
	v_sub_u32_e32 v7, v6, v4
	v_cndmask_b32_e32 v6, v6, v7, vcc
	v_cmp_ge_u32_e32 vcc, v6, v4
	v_add_u32_e32 v6, 1, v3
	s_nop 0
	v_cndmask_b32_e32 v3, v3, v6, vcc
	v_add_u32_e32 v6, 1, v5
	v_mad_u64_u32 v[4:5], s[8:9], v4, v3, v[4:5]
	v_cmp_ne_u32_e32 vcc, v6, v4
	s_and_saveexec_b64 s[8:9], vcc
	s_xor_b64 s[10:11], exec, s[8:9]
	s_cbranch_execz .LBB0_537
	v_sub_u32_e32 v2, v4, v6
	v_cmp_eq_u32_e32 vcc, 8, v2
	s_cbranch_vccz .Lef1_4_0
	buffer_wbl2 sc1
.Lef1_4_0:
	v_mov_b32_e32 v2, s7
	v_add_co_u32_e32 v4, vcc, 0x2000, v2
	v_mov_b32_e32 v2, s6
	s_nop 0
	v_addc_co_u32_e32 v5, vcc, 0, v2, vcc
	flat_load_dword v2, v[4:5] offset:1024 sc1
	s_add_u32 s66, s7, 0x2400
	s_addc_u32 s67, s6, 0
	s_waitcnt vmcnt(0) lgkmcnt(0)
	v_cmp_eq_u32_e32 vcc, v2, v3
	s_and_saveexec_b64 s[34:35], vcc
	s_cbranch_execz .LBB0_536
	s_mov_b32 s8, 1
	s_mov_b64 s[68:69], 0
	s_branch .LBB0_528
